# rmsnorm row loops software-pipelined: next row's loads in flight during the current row's reduce/scale/store
# speedup vs baseline: 1.0002x; 1.0002x over previous
.LBB0_100:
	v_readlane_b32 s2, v255, 30
	s_cmp_eq_u32 s2, 0
	s_cselect_b64 s[26:27], -1, 0
	v_readlane_b32 s3, v255, 31
	v_writelane_b32 v255, s26, 35
	s_lshl_b32 s2, s2, 10
	s_mov_b32 s3, s85
	v_writelane_b32 v255, s27, 36
	v_writelane_b32 v255, s2, 37
	v_mov_b32_e32 v0, v218
	v_mov_b32_e32 v1, v218
	v_writelane_b32 v255, s3, 38
	s_mov_b32 s2, s82
	s_lshl_b32 s40, s2, 2
	s_mov_b32 s2, 0x8000
	v_ashrrev_i32_e32 v18, 6, v1
	v_add_u32_e32 v20, s40, v18
	v_cmp_gt_i32_e32 vcc, s2, v20
	s_and_saveexec_b64 s[38:39], vcc
	v_readlane_b32 s42, v255, 22
	v_readlane_b32 s44, v255, 24
	v_readlane_b32 s43, v255, 23
	v_readlane_b32 s45, v255, 25
	s_mov_b32 s46, 0x800000
	s_movk_i32 s47, 0x7fff
	s_cbranch_execz .LBB0_103
	v_readlane_b32 s2, v255, 35
	v_readlane_b32 s3, v255, 36
	s_and_b64 s[2:3], s[2:3], exec
	s_load_dwordx2 s[2:3], s[36:37], 0x10
	s_cselect_b32 s25, 0, 0x90
	v_readlane_b32 s28, v255, 37
	s_add_u32 s26, s36, s25
	v_readlane_b32 s29, v255, 38
	s_addc_u32 s27, s37, 0
	s_lshl_b64 s[28:29], s[28:29], 2
	v_and_b32_e32 v21, 63, v0
	s_waitcnt lgkmcnt(0)
	s_add_u32 s2, s2, s28
	v_lshlrev_b32_e32 v24, 4, v21
	s_addc_u32 s3, s3, s29
	global_load_dwordx4 v[0:3], v24, s[2:3]
	global_load_dwordx4 v[4:7], v24, s[2:3] offset:1024
	global_load_dwordx4 v[8:11], v24, s[2:3] offset:2048
	global_load_dwordx4 v[12:15], v24, s[2:3] offset:3072
	s_load_dwordx2 s[2:3], s[26:27], 0x0
	v_ashrrev_i32_e32 v19, 31, v18
	s_ashr_i32 s41, s40, 31
	v_lshl_add_u64 v[18:19], v[18:19], 0, s[40:41]
	v_lshlrev_b64 v[22:23], 11, v[18:19]
	v_lshl_or_b32 v22, v21, 3, v22
	v_lshlrev_b64 v[18:19], 12, v[18:19]
	v_lshl_add_u64 v[16:17], v[16:17], 0, v[22:23]
	s_mov_b64 s[26:27], 0x400
	v_or_b32_e32 v18, v18, v24
	v_lshl_add_u64 v[16:17], v[16:17], 0, s[26:27]
	s_waitcnt lgkmcnt(0)
	v_lshl_add_u64 v[18:19], s[2:3], 0, v[18:19]
	s_mov_b64 s[36:37], 0
	global_load_dwordx4 v[54:57], v[18:19], off
	global_load_dwordx4 v[58:61], v[18:19], off offset:1024
	global_load_dwordx4 v[62:65], v[18:19], off offset:2048
	global_load_dwordx4 v[66:69], v[18:19], off offset:3072
	s_waitcnt vmcnt(0)
	s_branch .Lrn_entry_0
.LBB0_102:
	s_waitcnt vmcnt(4)
.Lrn_entry_0:
	v_mov_b64_e32 v[22:23], v[54:55]
	v_mov_b64_e32 v[24:25], v[56:57]
	v_mov_b64_e32 v[26:27], v[58:59]
	v_mov_b64_e32 v[28:29], v[60:61]
	v_mov_b64_e32 v[30:31], v[62:63]
	v_mov_b64_e32 v[32:33], v[64:65]
	v_mov_b64_e32 v[34:35], v[66:67]
	v_mov_b64_e32 v[36:37], v[68:69]
	v_add_u32_e32 v20, s54, v20
	v_lshl_add_u64 v[70:71], v[18:19], 0, s[44:45]
	v_cmp_lt_i32_e32 vcc, s47, v20
	s_nop 1
	v_cndmask_b32_e32 v18, v70, v18, vcc
	v_cndmask_b32_e32 v19, v71, v19, vcc
	global_load_dwordx4 v[54:57], v[18:19], off
	global_load_dwordx4 v[58:61], v[18:19], off offset:1024
	global_load_dwordx4 v[62:65], v[18:19], off offset:2048
	global_load_dwordx4 v[66:69], v[18:19], off offset:3072
	v_pk_mul_f32 v[40:41], v[22:23], v[22:23]
	v_pk_mul_f32 v[44:45], v[26:27], v[26:27]
	v_mov_b32_e32 v52, v31
	v_mov_b32_e32 v53, v35
	v_pk_mul_f32 v[38:39], v[24:25], v[24:25]
	v_pk_mul_f32 v[42:43], v[28:29], v[28:29]
	v_mov_b32_e32 v50, v30
	v_mov_b32_e32 v51, v34
	v_pk_mul_f32 v[52:53], v[52:53], v[52:53]
	v_add_f32_e32 v21, v44, v45
	v_add_f32_e32 v40, v40, v41
	v_mov_b32_e32 v46, v32
	v_mov_b32_e32 v47, v36
	v_pk_fma_f32 v[50:51], v[50:51], v[50:51], v[52:53]
	v_add_f32_e32 v21, v21, v42
	v_add_f32_e32 v38, v40, v38
	v_mov_b32_e32 v48, v33
	v_mov_b32_e32 v49, v37
	v_pk_fma_f32 v[46:47], v[46:47], v[46:47], v[50:51]
	v_add_f32_e32 v21, v21, v43
	v_add_f32_e32 v38, v38, v39
	v_pk_fma_f32 v[46:47], v[48:49], v[48:49], v[46:47]
	v_add_f32_e32 v21, v38, v21
	v_add_f32_e32 v21, v21, v46
	v_add_f32_e32 v21, v21, v47
	s_nop 1
	v_add_f32_dpp v21, v21, v21 row_ror:8 row_mask:0xf bank_mask:0xf bound_ctrl:1
	s_nop 1
	v_add_f32_dpp v21, v21, v21 row_ror:4 row_mask:0xf bank_mask:0xf bound_ctrl:1
	s_nop 1
	v_add_f32_dpp v21, v21, v21 quad_perm:[2,3,0,1] row_mask:0xf bank_mask:0xf bound_ctrl:1
	s_nop 1
	v_add_f32_dpp v21, v21, v21 quad_perm:[1,0,3,2] row_mask:0xf bank_mask:0xf bound_ctrl:1
	s_nop 0
	v_readlane_b32 s3, v21, 16
	v_readlane_b32 s2, v21, 0
	s_nop 0
	v_mov_b32_e32 v38, s3
	v_add_f32_e32 v38, s2, v38
	v_readlane_b32 s2, v21, 32
	s_nop 1
	v_add_f32_e32 v38, s2, v38
	v_readlane_b32 s2, v21, 48
	s_nop 1
	v_add_f32_e32 v21, s2, v38
	v_fmamk_f32 v21, v21, 0x3a800000, v220
	v_cmp_gt_f32_e32 vcc, s46, v21
	v_mul_f32_e32 v38, 0x4b800000, v21
	s_nop 0
	v_cndmask_b32_e32 v21, v21, v38, vcc
	v_rsq_f32_e32 v21, v21
	s_nop 0
	v_mul_f32_e32 v38, 0x45800000, v21
	v_cndmask_b32_e32 v38, v21, v38, vcc
	v_pk_mul_f32 v[22:23], v[22:23], v[38:39] op_sel_hi:[1,0]
	v_pk_mul_f32 v[24:25], v[24:25], v[38:39] op_sel_hi:[1,0]
	v_pk_mul_f32 v[22:23], v[0:1], v[22:23]
	v_pk_mul_f32 v[24:25], v[2:3], v[24:25]
	v_cvt_pk_bf16_f32 v22, v22, v23
	v_cvt_pk_bf16_f32 v23, v24, v25
	global_store_dwordx2 v[16:17], v[22:23], off offset:-1024
	v_pk_mul_f32 v[22:23], v[26:27], v[38:39] op_sel_hi:[1,0]
	v_pk_mul_f32 v[24:25], v[28:29], v[38:39] op_sel_hi:[1,0]
	v_pk_mul_f32 v[22:23], v[4:5], v[22:23]
	v_pk_mul_f32 v[24:25], v[6:7], v[24:25]
	v_cvt_pk_bf16_f32 v22, v22, v23
	v_cvt_pk_bf16_f32 v23, v24, v25
	global_store_dwordx2 v[16:17], v[22:23], off offset:-512
	v_pk_mul_f32 v[22:23], v[30:31], v[38:39] op_sel_hi:[1,0]
	v_pk_mul_f32 v[24:25], v[32:33], v[38:39] op_sel_hi:[1,0]
	v_pk_mul_f32 v[22:23], v[8:9], v[22:23]
	v_pk_mul_f32 v[24:25], v[10:11], v[24:25]
	v_cvt_pk_bf16_f32 v22, v22, v23
	v_cvt_pk_bf16_f32 v23, v24, v25
	global_store_dwordx2 v[16:17], v[22:23], off
	v_pk_mul_f32 v[22:23], v[34:35], v[38:39] op_sel_hi:[1,0]
	v_pk_mul_f32 v[24:25], v[36:37], v[38:39] op_sel_hi:[1,0]
	v_pk_mul_f32 v[22:23], v[12:13], v[22:23]
	v_pk_mul_f32 v[24:25], v[14:15], v[24:25]
	v_cvt_pk_bf16_f32 v22, v22, v23
	v_cvt_pk_bf16_f32 v23, v24, v25
	v_cmp_lt_i32_e32 vcc, s47, v20
	global_store_dwordx2 v[16:17], v[22:23], off offset:512
	v_lshl_add_u64 v[16:17], v[16:17], 0, s[42:43]
	s_or_b64 s[36:37], vcc, s[36:37]
	s_andn2_b64 exec, exec, s[36:37]
	s_cbranch_execnz .LBB0_102

.LBB0_1030:
	s_or_b64 exec, exec, s[36:37]
	v_readlane_b32 s40, v254, 0
	v_readlane_b32 s41, v254, 1
	s_waitcnt lgkmcnt(0)
	v_mov_b32_e32 v0, v218
	s_mov_b32 s2, s82
	v_mov_b32_e32 v1, v218
	s_barrier
	s_lshl_b32 s38, s2, 2
	s_mov_b32 s2, 0x8000
	v_ashrrev_i32_e32 v16, 6, v1
	v_add_u32_e32 v20, s38, v16
	v_cmp_gt_i32_e32 vcc, s2, v20
	s_and_saveexec_b64 s[36:37], vcc
	v_readlane_b32 s28, v255, 22
	v_readlane_b32 s42, v255, 24
	v_readlane_b32 s29, v255, 23
	v_readlane_b32 s43, v255, 25
	s_mov_b32 s25, 0x800000
	s_movk_i32 s48, 0x7fff
	s_cbranch_execz .LBB0_1033
	s_load_dwordx2 s[2:3], s[40:41], 0x78
	v_readlane_b32 s26, v255, 37
	v_readlane_b32 s27, v255, 38
	s_lshl_b64 s[26:27], s[26:27], 2
	v_and_b32_e32 v21, 63, v0
	s_waitcnt lgkmcnt(0)
	s_add_u32 s2, s2, s26
	v_lshlrev_b32_e32 v22, 4, v21
	s_addc_u32 s3, s3, s27
	global_load_dwordx4 v[0:3], v22, s[2:3]
	global_load_dwordx4 v[4:7], v22, s[2:3] offset:1024
	global_load_dwordx4 v[8:11], v22, s[2:3] offset:2048
	global_load_dwordx4 v[12:15], v22, s[2:3] offset:3072
	s_load_dwordx4 s[44:47], s[40:41], 0x90
	v_ashrrev_i32_e32 v17, 31, v16
	s_ashr_i32 s39, s38, 31
	v_lshl_add_u64 v[18:19], v[16:17], 0, s[38:39]
	v_lshlrev_b64 v[16:17], 11, v[18:19]
	v_lshl_or_b32 v16, v21, 3, v16
	v_lshlrev_b64 v[18:19], 12, v[18:19]
	s_waitcnt lgkmcnt(0)
	v_lshl_add_u64 v[16:17], s[46:47], 0, v[16:17]
	s_mov_b64 s[2:3], 0x400
	v_or_b32_e32 v18, v18, v22
	v_lshl_add_u64 v[16:17], v[16:17], 0, s[2:3]
	v_lshl_add_u64 v[18:19], s[44:45], 0, v[18:19]
	s_mov_b64 s[38:39], 0
	global_load_dwordx4 v[54:57], v[18:19], off
	global_load_dwordx4 v[58:61], v[18:19], off offset:1024
	global_load_dwordx4 v[62:65], v[18:19], off offset:2048
	global_load_dwordx4 v[66:69], v[18:19], off offset:3072
	s_waitcnt vmcnt(0)
	s_branch .Lrn_entry_1

.Lrn_entry_1:
	v_mov_b64_e32 v[22:23], v[54:55]
	v_mov_b64_e32 v[24:25], v[56:57]
	v_mov_b64_e32 v[26:27], v[58:59]
	v_mov_b64_e32 v[28:29], v[60:61]
	v_mov_b64_e32 v[30:31], v[62:63]
	v_mov_b64_e32 v[32:33], v[64:65]
	v_mov_b64_e32 v[34:35], v[66:67]
	v_mov_b64_e32 v[36:37], v[68:69]
	v_add_u32_e32 v20, s54, v20
	v_lshl_add_u64 v[70:71], v[18:19], 0, s[42:43]
	v_cmp_lt_i32_e32 vcc, s48, v20
	s_nop 1
	v_cndmask_b32_e32 v18, v70, v18, vcc
	v_cndmask_b32_e32 v19, v71, v19, vcc
	global_load_dwordx4 v[54:57], v[18:19], off
	global_load_dwordx4 v[58:61], v[18:19], off offset:1024
	global_load_dwordx4 v[62:65], v[18:19], off offset:2048
	global_load_dwordx4 v[66:69], v[18:19], off offset:3072
	v_pk_mul_f32 v[40:41], v[22:23], v[22:23]
	v_pk_mul_f32 v[44:45], v[26:27], v[26:27]
	v_mov_b32_e32 v52, v31
	v_mov_b32_e32 v53, v35
	v_pk_mul_f32 v[38:39], v[24:25], v[24:25]
	v_pk_mul_f32 v[42:43], v[28:29], v[28:29]
	v_mov_b32_e32 v50, v30
	v_mov_b32_e32 v51, v34
	v_pk_mul_f32 v[52:53], v[52:53], v[52:53]
	v_add_f32_e32 v21, v44, v45
	v_add_f32_e32 v40, v40, v41
	v_mov_b32_e32 v46, v32
	v_mov_b32_e32 v47, v36
	v_pk_fma_f32 v[50:51], v[50:51], v[50:51], v[52:53]
	v_add_f32_e32 v21, v21, v42
	v_add_f32_e32 v38, v40, v38
	v_mov_b32_e32 v48, v33
	v_mov_b32_e32 v49, v37
	v_pk_fma_f32 v[46:47], v[46:47], v[46:47], v[50:51]
	v_add_f32_e32 v21, v21, v43
	v_add_f32_e32 v38, v38, v39
	v_pk_fma_f32 v[46:47], v[48:49], v[48:49], v[46:47]
	v_add_f32_e32 v21, v38, v21
	v_add_f32_e32 v21, v21, v46
	v_add_f32_e32 v21, v21, v47
	s_nop 1
	v_add_f32_dpp v21, v21, v21 row_ror:8 row_mask:0xf bank_mask:0xf bound_ctrl:1
	s_nop 1
	v_add_f32_dpp v21, v21, v21 row_ror:4 row_mask:0xf bank_mask:0xf bound_ctrl:1
	s_nop 1
	v_add_f32_dpp v21, v21, v21 quad_perm:[2,3,0,1] row_mask:0xf bank_mask:0xf bound_ctrl:1
	s_nop 1
	v_add_f32_dpp v21, v21, v21 quad_perm:[1,0,3,2] row_mask:0xf bank_mask:0xf bound_ctrl:1
	s_nop 0
	v_readlane_b32 s3, v21, 16
	v_readlane_b32 s2, v21, 0
	s_nop 0
	v_mov_b32_e32 v38, s3
	v_add_f32_e32 v38, s2, v38
	v_readlane_b32 s2, v21, 32
	s_nop 1
	v_add_f32_e32 v38, s2, v38
	v_readlane_b32 s2, v21, 48
	s_nop 1
	v_add_f32_e32 v21, s2, v38
	v_fmamk_f32 v21, v21, 0x3a800000, v220
	v_cmp_gt_f32_e32 vcc, s25, v21
	v_mul_f32_e32 v38, 0x4b800000, v21
	s_nop 0
	v_cndmask_b32_e32 v21, v21, v38, vcc
	v_rsq_f32_e32 v21, v21
	s_nop 0
	v_mul_f32_e32 v38, 0x45800000, v21
	v_cndmask_b32_e32 v38, v21, v38, vcc
	v_pk_mul_f32 v[22:23], v[22:23], v[38:39] op_sel_hi:[1,0]
	v_pk_mul_f32 v[24:25], v[24:25], v[38:39] op_sel_hi:[1,0]
	v_pk_mul_f32 v[22:23], v[0:1], v[22:23]
	v_pk_mul_f32 v[24:25], v[2:3], v[24:25]
	v_cvt_pk_bf16_f32 v22, v22, v23
	v_cvt_pk_bf16_f32 v23, v24, v25
	global_store_dwordx2 v[16:17], v[22:23], off offset:-1024
	v_pk_mul_f32 v[22:23], v[26:27], v[38:39] op_sel_hi:[1,0]
	v_pk_mul_f32 v[24:25], v[28:29], v[38:39] op_sel_hi:[1,0]
	v_pk_mul_f32 v[22:23], v[4:5], v[22:23]
	v_pk_mul_f32 v[24:25], v[6:7], v[24:25]
	v_cvt_pk_bf16_f32 v22, v22, v23
	v_cvt_pk_bf16_f32 v23, v24, v25
	global_store_dwordx2 v[16:17], v[22:23], off offset:-512
	v_pk_mul_f32 v[22:23], v[30:31], v[38:39] op_sel_hi:[1,0]
	v_pk_mul_f32 v[24:25], v[32:33], v[38:39] op_sel_hi:[1,0]
	v_pk_mul_f32 v[22:23], v[8:9], v[22:23]
	v_pk_mul_f32 v[24:25], v[10:11], v[24:25]
	v_cvt_pk_bf16_f32 v22, v22, v23
	v_cvt_pk_bf16_f32 v23, v24, v25
	global_store_dwordx2 v[16:17], v[22:23], off
	v_pk_mul_f32 v[22:23], v[34:35], v[38:39] op_sel_hi:[1,0]
	v_pk_mul_f32 v[24:25], v[36:37], v[38:39] op_sel_hi:[1,0]
	v_pk_mul_f32 v[22:23], v[12:13], v[22:23]
	v_pk_mul_f32 v[24:25], v[14:15], v[24:25]
	v_cvt_pk_bf16_f32 v22, v22, v23
	v_cvt_pk_bf16_f32 v23, v24, v25
	v_cmp_lt_i32_e32 vcc, s48, v20
	global_store_dwordx2 v[16:17], v[22:23], off offset:512
	v_lshl_add_u64 v[16:17], v[16:17], 0, s[28:29]
	s_or_b64 s[38:39], vcc, s[38:39]
	s_andn2_b64 exec, exec, s[38:39]
	s_cbranch_execnz .LBB0_1032
